# B-layer in-GEMM silu (gate) tiles, which are every workgroup's last two units of the phase, stored write-through (sc1) to thin the dirty L2 at the following grid barrier
# speedup vs baseline: 1.0021x; 1.0021x over previous
.Lssq_b_cached:
	v_mov_b32_e32 v136, v243
	v_mov_b32_e32 v194, v244
	v_mov_b32_e32 v211, v245
	v_mov_b32_e32 v210, v246
	v_mov_b32_e32 v209, v247
	v_mov_b32_e32 v208, v248
	v_mov_b32_e32 v207, v249
	v_mov_b32_e32 v206, v250
	v_add_u32_e32 v188, 0x80, v186
	s_mov_b64 s[12:13], -1
	v_ashrrev_i32_e32 v189, 31, v188
	s_andn2_b64 vcc, exec, s[0:1]
	s_nop 0
	v_fmamk_f32 v133, v136, 0x3a000000, v200
	v_cmp_gt_f32_e64 s[0:1], s91, v133
	v_mul_f32_e32 v146, 0x4b800000, v133
	s_cbranch_vccz .LBB0_646
	v_cndmask_b32_e64 v132, v133, v146, s[0:1]
	v_rsq_f32_e32 v132, v132
	s_xor_b64 s[10:11], s[10:11], -1
	s_and_b64 vcc, exec, s[10:11]
	v_mul_f32_e32 v134, 0x45800000, v132
	v_cndmask_b32_e64 v132, v132, v134, s[0:1]
	s_mov_b64 s[0:1], -1
	s_cbranch_vccz .LBB0_640
	v_pk_mul_f32 v[150:151], v[128:129], v[132:133] op_sel_hi:[1,0]
	v_pk_mul_f32 v[154:155], v[124:125], v[132:133] op_sel_hi:[1,0]
	v_mul_f32_e32 v147, 0xbfb8aa3b, v150
	v_exp_f32_e32 v147, v147
	v_pk_mul_f32 v[148:149], v[130:131], v[132:133] op_sel_hi:[1,0]
	v_pk_mul_f32 v[152:153], v[126:127], v[132:133] op_sel_hi:[1,0]
	v_lshl_or_b32 v136, s9, 8, v176
	v_add_f32_e32 v147, 1.0, v147
	v_rcp_f32_e32 v147, v147
	v_ashrrev_i32_e32 v137, 31, v136
	v_lshl_add_u64 v[136:137], v[136:137], 1, s[26:27]
	v_lshlrev_b64 v[144:145], 12, v[186:187]
	v_mul_f32_e32 v147, v150, v147
	v_mul_f32_e32 v150, 0xbfb8aa3b, v154
	v_exp_f32_e32 v150, v150
	v_lshl_add_u64 v[144:145], v[136:137], 0, v[144:145]
	v_lshlrev_b64 v[142:143], 12, v[142:143]
	v_lshl_add_u64 v[142:143], v[136:137], 0, v[142:143]
	v_add_f32_e32 v150, 1.0, v150
	v_rcp_f32_e32 v150, v150
	v_lshlrev_b64 v[140:141], 12, v[140:141]
	v_lshl_add_u64 v[140:141], v[136:137], 0, v[140:141]
	v_lshlrev_b64 v[138:139], 12, v[138:139]
	v_mul_f32_e32 v150, v154, v150
	v_mul_f32_e32 v154, 0xbfb8aa3b, v151
	v_exp_f32_e32 v154, v154
	v_lshl_add_u64 v[138:139], v[136:137], 0, v[138:139]
	v_lshlrev_b64 v[134:135], 12, v[186:187]
	v_lshl_add_u64 v[134:135], v[136:137], 0, v[134:135]
	v_add_f32_e32 v154, 1.0, v154
	v_rcp_f32_e32 v154, v154
	s_mov_b64 s[0:1], 0x90000
	v_mul_f32_e32 v151, v151, v154
	v_mul_f32_e32 v154, 0xbfb8aa3b, v155
	v_exp_f32_e32 v154, v154
	s_nop 0
	v_add_f32_e32 v154, 1.0, v154
	v_rcp_f32_e32 v154, v154
	s_nop 0
	v_mul_f32_e32 v154, v155, v154
	v_mul_f32_e32 v155, 0xbfb8aa3b, v148
	v_exp_f32_e32 v155, v155
	s_nop 0
	v_add_f32_e32 v155, 1.0, v155
	v_rcp_f32_e32 v155, v155
	s_nop 0
	v_mul_f32_e32 v155, v148, v155
	v_mul_f32_e32 v148, 0xbfb8aa3b, v152
	v_exp_f32_e32 v148, v148
	s_nop 0
	v_add_f32_e32 v148, 1.0, v148
	v_rcp_f32_e32 v148, v148
	s_nop 0
	v_mul_f32_e32 v152, v152, v148
	v_mul_f32_e32 v148, 0xbfb8aa3b, v149
	v_exp_f32_e32 v148, v148
	s_nop 0
	v_add_f32_e32 v148, 1.0, v148
	v_rcp_f32_e32 v148, v148
	s_nop 0
	v_mul_f32_e32 v149, v149, v148
	v_mul_f32_e32 v148, 0xbfb8aa3b, v153
	v_exp_f32_e32 v148, v148
	s_nop 0
	v_add_f32_e32 v148, 1.0, v148
	v_rcp_f32_e32 v148, v148
	s_nop 0
	v_mul_f32_e32 v153, v153, v148
	v_cvt_pk_bf16_f32 v148, v147, v151
	v_cvt_pk_bf16_f32 v149, v155, v149
	v_cvt_pk_bf16_f32 v150, v150, v154
	v_cvt_pk_bf16_f32 v151, v152, v153
	global_store_dwordx4 v[144:145], v[148:151], off sc1
	v_pk_mul_f32 v[154:155], v[92:93], v[132:133] op_sel_hi:[1,0]
	v_pk_mul_f32 v[152:153], v[94:95], v[132:133] op_sel_hi:[1,0]
	v_pk_mul_f32 v[150:151], v[96:97], v[132:133] op_sel_hi:[1,0]
	v_pk_mul_f32 v[148:149], v[98:99], v[132:133] op_sel_hi:[1,0]
	v_mul_f32_e32 v147, 0xbfb8aa3b, v150
	v_exp_f32_e32 v147, v147
	s_nop 0
	v_add_f32_e32 v147, 1.0, v147
	v_rcp_f32_e32 v147, v147
	s_nop 0
	v_mul_f32_e32 v147, v150, v147
	v_mul_f32_e32 v150, 0xbfb8aa3b, v154
	v_exp_f32_e32 v150, v150
	s_nop 0
	v_add_f32_e32 v150, 1.0, v150
	v_rcp_f32_e32 v150, v150
	s_nop 0
	v_mul_f32_e32 v150, v154, v150
	v_mul_f32_e32 v154, 0xbfb8aa3b, v151
	v_exp_f32_e32 v154, v154
	s_nop 0
	v_add_f32_e32 v154, 1.0, v154
	v_rcp_f32_e32 v154, v154
	s_nop 0
	v_mul_f32_e32 v151, v151, v154
	v_mul_f32_e32 v154, 0xbfb8aa3b, v155
	v_exp_f32_e32 v154, v154
	s_nop 0
	v_add_f32_e32 v154, 1.0, v154
	v_rcp_f32_e32 v154, v154
	s_nop 0
	v_mul_f32_e32 v154, v155, v154
	v_mul_f32_e32 v155, 0xbfb8aa3b, v148
	v_exp_f32_e32 v155, v155
	s_nop 0
	v_add_f32_e32 v155, 1.0, v155
	v_rcp_f32_e32 v155, v155
	s_nop 0
	v_mul_f32_e32 v155, v148, v155
	v_mul_f32_e32 v148, 0xbfb8aa3b, v152
	v_exp_f32_e32 v148, v148
	s_nop 0
	v_add_f32_e32 v148, 1.0, v148
	v_rcp_f32_e32 v148, v148
	s_nop 0
	v_mul_f32_e32 v152, v152, v148
	v_mul_f32_e32 v148, 0xbfb8aa3b, v149
	v_exp_f32_e32 v148, v148
	s_nop 0
	v_add_f32_e32 v148, 1.0, v148
	v_rcp_f32_e32 v148, v148
	s_nop 0
	v_mul_f32_e32 v149, v149, v148
	v_mul_f32_e32 v148, 0xbfb8aa3b, v153
	v_exp_f32_e32 v148, v148
	s_nop 0
	v_add_f32_e32 v148, 1.0, v148
	v_rcp_f32_e32 v148, v148
	s_nop 0
	v_mul_f32_e32 v153, v153, v148
	v_cvt_pk_bf16_f32 v148, v147, v151
	v_cvt_pk_bf16_f32 v149, v155, v149
	v_cvt_pk_bf16_f32 v150, v150, v154
	v_cvt_pk_bf16_f32 v151, v152, v153
	global_store_dwordx4 v[144:145], v[148:151], off offset:256 sc1
	v_fmamk_f32 v144, v194, 0x3a000000, v200
	v_cmp_gt_f32_e32 vcc, s91, v144
	v_mul_f32_e32 v145, 0x4b800000, v144
	s_nop 0
	v_cndmask_b32_e32 v144, v144, v145, vcc
	v_rsq_f32_e32 v144, v144
	s_nop 0
	v_mul_f32_e32 v145, 0x45800000, v144
	v_cndmask_b32_e32 v144, v144, v145, vcc
	v_pk_mul_f32 v[154:155], v[116:117], v[144:145] op_sel_hi:[1,0]
	v_pk_mul_f32 v[148:149], v[122:123], v[144:145] op_sel_hi:[1,0]
	v_mul_f32_e32 v147, 0xbfb8aa3b, v154
	v_exp_f32_e32 v147, v147
	v_pk_mul_f32 v[150:151], v[120:121], v[144:145] op_sel_hi:[1,0]
	v_pk_mul_f32 v[152:153], v[118:119], v[144:145] op_sel_hi:[1,0]
	v_mul_f32_e32 v145, 0xbfb8aa3b, v150
	v_add_f32_e32 v147, 1.0, v147
	v_rcp_f32_e32 v147, v147
	v_exp_f32_e32 v145, v145
	v_mul_f32_e32 v147, v154, v147
	v_mul_f32_e32 v154, 0xbfb8aa3b, v148
	v_exp_f32_e32 v154, v154
	v_add_f32_e32 v145, 1.0, v145
	v_rcp_f32_e32 v145, v145
	v_add_f32_e32 v154, 1.0, v154
	v_rcp_f32_e32 v154, v154
	v_mul_f32_e32 v145, v150, v145
	v_mul_f32_e32 v150, 0xbfb8aa3b, v151
	v_exp_f32_e32 v150, v150
	v_mul_f32_e32 v154, v148, v154
	v_mul_f32_e32 v148, 0xbfb8aa3b, v152
	v_exp_f32_e32 v148, v148
	v_add_f32_e32 v150, 1.0, v150
	v_rcp_f32_e32 v150, v150
	v_add_f32_e32 v148, 1.0, v148
	v_rcp_f32_e32 v148, v148
	v_mul_f32_e32 v150, v151, v150
	v_mul_f32_e32 v151, 0xbfb8aa3b, v155
	v_exp_f32_e32 v151, v151
	v_mul_f32_e32 v152, v152, v148
	v_mul_f32_e32 v148, 0xbfb8aa3b, v149
	v_exp_f32_e32 v148, v148
	v_add_f32_e32 v151, 1.0, v151
	v_rcp_f32_e32 v151, v151
	v_add_f32_e32 v148, 1.0, v148
	v_rcp_f32_e32 v148, v148
	v_mul_f32_e32 v151, v155, v151
	v_mul_f32_e32 v149, v149, v148
	v_mul_f32_e32 v148, 0xbfb8aa3b, v153
	v_exp_f32_e32 v148, v148
	s_nop 0
	v_add_f32_e32 v148, 1.0, v148
	v_rcp_f32_e32 v148, v148
	s_nop 0
	v_mul_f32_e32 v153, v153, v148
	v_cvt_pk_bf16_f32 v148, v145, v150
	v_cvt_pk_bf16_f32 v149, v154, v149
	v_cvt_pk_bf16_f32 v150, v147, v151
	v_cvt_pk_bf16_f32 v151, v152, v153
	global_store_dwordx4 v[142:143], v[148:151], off sc1
	v_pk_mul_f32 v[152:153], v[86:87], v[144:145] op_sel_hi:[1,0]
	s_nop 0
	v_pk_mul_f32 v[150:151], v[88:89], v[144:145] op_sel_hi:[1,0]
	v_pk_mul_f32 v[148:149], v[90:91], v[144:145] op_sel_hi:[1,0]
	v_mul_f32_e32 v147, 0xbfb8aa3b, v150
	v_exp_f32_e32 v147, v147
	v_pk_mul_f32 v[144:145], v[84:85], v[144:145] op_sel_hi:[1,0]
	v_add_f32_e32 v147, 1.0, v147
	v_rcp_f32_e32 v147, v147
	s_nop 0
	v_mul_f32_e32 v147, v150, v147
	v_mul_f32_e32 v150, 0xbfb8aa3b, v144
	v_exp_f32_e32 v150, v150
	s_nop 0
	v_add_f32_e32 v150, 1.0, v150
	v_rcp_f32_e32 v150, v150
	s_nop 0
	v_mul_f32_e32 v144, v144, v150
	v_mul_f32_e32 v150, 0xbfb8aa3b, v151
	v_exp_f32_e32 v150, v150
	s_nop 0
	v_add_f32_e32 v150, 1.0, v150
	v_rcp_f32_e32 v150, v150
	s_nop 0
	v_mul_f32_e32 v150, v151, v150
	v_mul_f32_e32 v151, 0xbfb8aa3b, v145
	v_exp_f32_e32 v151, v151
	s_nop 0
	v_add_f32_e32 v151, 1.0, v151
	v_rcp_f32_e32 v151, v151
	s_nop 0
	v_mul_f32_e32 v145, v145, v151
	v_mul_f32_e32 v151, 0xbfb8aa3b, v148
	v_exp_f32_e32 v151, v151
	s_nop 0
	v_add_f32_e32 v151, 1.0, v151
	v_rcp_f32_e32 v151, v151
	s_nop 0
	v_mul_f32_e32 v151, v148, v151
	v_mul_f32_e32 v148, 0xbfb8aa3b, v152
	v_exp_f32_e32 v148, v148
	s_nop 0
	v_add_f32_e32 v148, 1.0, v148
	v_rcp_f32_e32 v148, v148
	s_nop 0
	v_mul_f32_e32 v152, v152, v148
	v_mul_f32_e32 v148, 0xbfb8aa3b, v149
	v_exp_f32_e32 v148, v148
	s_nop 0
	v_add_f32_e32 v148, 1.0, v148
	v_rcp_f32_e32 v148, v148
	s_nop 0
	v_mul_f32_e32 v149, v149, v148
	v_mul_f32_e32 v148, 0xbfb8aa3b, v153
	v_exp_f32_e32 v148, v148
	s_nop 0
	v_add_f32_e32 v148, 1.0, v148
	v_rcp_f32_e32 v148, v148
	s_nop 0
	v_mul_f32_e32 v153, v153, v148
	v_cvt_pk_bf16_f32 v148, v147, v150
	v_cvt_pk_bf16_f32 v149, v151, v149
	v_cvt_pk_bf16_f32 v150, v144, v145
	v_cvt_pk_bf16_f32 v151, v152, v153
	global_store_dwordx4 v[142:143], v[148:151], off offset:256 sc1
	v_fmamk_f32 v142, v211, 0x3a000000, v200
	v_cmp_gt_f32_e32 vcc, s91, v142
	v_mul_f32_e32 v143, 0x4b800000, v142
	s_nop 0
	v_cndmask_b32_e32 v142, v142, v143, vcc
	v_rsq_f32_e32 v142, v142
	s_nop 0
	v_mul_f32_e32 v143, 0x45800000, v142
	v_cndmask_b32_e32 v148, v142, v143, vcc
	v_pk_mul_f32 v[144:145], v[112:113], v[148:149] op_sel_hi:[1,0]
	v_pk_mul_f32 v[152:153], v[108:109], v[148:149] op_sel_hi:[1,0]
	v_mul_f32_e32 v147, 0xbfb8aa3b, v144
	v_exp_f32_e32 v147, v147
	v_pk_mul_f32 v[142:143], v[114:115], v[148:149] op_sel_hi:[1,0]
	v_pk_mul_f32 v[150:151], v[110:111], v[148:149] op_sel_hi:[1,0]
	v_mul_f32_e32 v149, 0xbfb8aa3b, v145
	v_add_f32_e32 v147, 1.0, v147
	v_rcp_f32_e32 v147, v147
	v_exp_f32_e32 v149, v149
	v_mul_f32_e32 v144, v144, v147
	v_mul_f32_e32 v147, 0xbfb8aa3b, v152
	v_exp_f32_e32 v147, v147
	v_add_f32_e32 v149, 1.0, v149
	v_rcp_f32_e32 v149, v149
	v_add_f32_e32 v147, 1.0, v147
	v_rcp_f32_e32 v147, v147
	v_mul_f32_e32 v145, v145, v149
	v_mul_f32_e32 v149, 0xbfb8aa3b, v153
	v_exp_f32_e32 v149, v149
	v_mul_f32_e32 v147, v152, v147
	v_mul_f32_e32 v152, 0xbfb8aa3b, v142
	v_exp_f32_e32 v152, v152
	v_add_f32_e32 v149, 1.0, v149
	v_rcp_f32_e32 v149, v149
	v_add_f32_e32 v152, 1.0, v152
	v_rcp_f32_e32 v152, v152
	v_mul_f32_e32 v149, v153, v149
	v_mul_f32_e32 v152, v142, v152
	v_mul_f32_e32 v142, 0xbfb8aa3b, v150
	v_exp_f32_e32 v142, v142
	s_nop 0
	v_add_f32_e32 v142, 1.0, v142
	v_rcp_f32_e32 v142, v142
	s_nop 0
	v_mul_f32_e32 v150, v150, v142
	v_mul_f32_e32 v142, 0xbfb8aa3b, v143
	v_exp_f32_e32 v142, v142
	s_nop 0
	v_add_f32_e32 v142, 1.0, v142
	v_rcp_f32_e32 v142, v142
	s_nop 0
	v_mul_f32_e32 v143, v143, v142
	v_mul_f32_e32 v142, 0xbfb8aa3b, v151
	v_exp_f32_e32 v142, v142
	s_nop 0
	v_add_f32_e32 v142, 1.0, v142
	v_rcp_f32_e32 v142, v142
	s_nop 0
	v_mul_f32_e32 v151, v151, v142
	v_cvt_pk_bf16_f32 v142, v144, v145
	v_cvt_pk_bf16_f32 v143, v152, v143
	v_cvt_pk_bf16_f32 v144, v147, v149
	v_cvt_pk_bf16_f32 v145, v150, v151
	global_store_dwordx4 v[140:141], v[142:145], off sc1
	v_pk_mul_f32 v[150:151], v[78:79], v[148:149] op_sel_hi:[1,0]
	s_nop 0
	v_pk_mul_f32 v[144:145], v[80:81], v[148:149] op_sel_hi:[1,0]
	v_pk_mul_f32 v[142:143], v[82:83], v[148:149] op_sel_hi:[1,0]
	v_mul_f32_e32 v147, 0xbfb8aa3b, v144
	v_exp_f32_e32 v147, v147
	v_pk_mul_f32 v[148:149], v[76:77], v[148:149] op_sel_hi:[1,0]
	v_add_f32_e32 v147, 1.0, v147
	v_rcp_f32_e32 v147, v147
	s_nop 0
	v_mul_f32_e32 v144, v144, v147
	v_mul_f32_e32 v147, 0xbfb8aa3b, v148
	v_exp_f32_e32 v147, v147
	s_nop 0
	v_add_f32_e32 v147, 1.0, v147
	v_rcp_f32_e32 v147, v147
	s_nop 0
	v_mul_f32_e32 v147, v148, v147
	v_mul_f32_e32 v148, 0xbfb8aa3b, v145
	v_exp_f32_e32 v148, v148
	s_nop 0
	v_add_f32_e32 v148, 1.0, v148
	v_rcp_f32_e32 v148, v148
	s_nop 0
	v_mul_f32_e32 v145, v145, v148
	v_mul_f32_e32 v148, 0xbfb8aa3b, v149
	v_exp_f32_e32 v148, v148
	s_nop 0
	v_add_f32_e32 v148, 1.0, v148
	v_rcp_f32_e32 v148, v148
	s_nop 0
	v_mul_f32_e32 v148, v149, v148
	v_mul_f32_e32 v149, 0xbfb8aa3b, v142
	v_exp_f32_e32 v149, v149
	s_nop 0
	v_add_f32_e32 v149, 1.0, v149
	v_rcp_f32_e32 v149, v149
	s_nop 0
	v_mul_f32_e32 v149, v142, v149
	v_mul_f32_e32 v142, 0xbfb8aa3b, v150
	v_exp_f32_e32 v142, v142
	s_nop 0
	v_add_f32_e32 v142, 1.0, v142
	v_rcp_f32_e32 v142, v142
	s_nop 0
	v_mul_f32_e32 v150, v150, v142
	v_mul_f32_e32 v142, 0xbfb8aa3b, v143
	v_exp_f32_e32 v142, v142
	s_nop 0
	v_add_f32_e32 v142, 1.0, v142
	v_rcp_f32_e32 v142, v142
	s_nop 0
	v_mul_f32_e32 v143, v143, v142
	v_mul_f32_e32 v142, 0xbfb8aa3b, v151
	v_exp_f32_e32 v142, v142
	s_nop 0
	v_add_f32_e32 v142, 1.0, v142
	v_rcp_f32_e32 v142, v142
	s_nop 0
	v_mul_f32_e32 v151, v151, v142
	v_cvt_pk_bf16_f32 v142, v144, v145
	v_cvt_pk_bf16_f32 v143, v149, v143
	v_cvt_pk_bf16_f32 v144, v147, v148
	v_cvt_pk_bf16_f32 v145, v150, v151
	global_store_dwordx4 v[140:141], v[142:145], off offset:256 sc1
	v_fmamk_f32 v140, v210, 0x3a000000, v200
	v_cmp_gt_f32_e32 vcc, s91, v140
	v_mul_f32_e32 v141, 0x4b800000, v140
	s_nop 0
	v_cndmask_b32_e32 v140, v140, v141, vcc
	v_rsq_f32_e32 v140, v140
	s_nop 0
	v_mul_f32_e32 v141, 0x45800000, v140
	v_cndmask_b32_e32 v144, v140, v141, vcc
	v_pk_mul_f32 v[142:143], v[104:105], v[144:145] op_sel_hi:[1,0]
	v_pk_mul_f32 v[140:141], v[106:107], v[144:145] op_sel_hi:[1,0]
	v_pk_mul_f32 v[148:149], v[102:103], v[144:145] op_sel_hi:[1,0]
	v_pk_mul_f32 v[150:151], v[100:101], v[144:145] op_sel_hi:[1,0]
	v_mul_f32_e32 v145, 0xbfb8aa3b, v142
	v_exp_f32_e32 v145, v145
	v_mul_f32_e32 v147, 0xbfb8aa3b, v143
	v_exp_f32_e32 v147, v147
	v_add_f32_e32 v145, 1.0, v145
	v_rcp_f32_e32 v145, v145
	v_add_f32_e32 v147, 1.0, v147
	v_rcp_f32_e32 v147, v147
	v_mul_f32_e32 v142, v142, v145
	v_mul_f32_e32 v145, 0xbfb8aa3b, v150
	v_exp_f32_e32 v145, v145
	v_mul_f32_e32 v143, v143, v147
	v_mul_f32_e32 v147, 0xbfb8aa3b, v151
	v_exp_f32_e32 v147, v147
	v_add_f32_e32 v145, 1.0, v145
	v_rcp_f32_e32 v145, v145
	v_add_f32_e32 v147, 1.0, v147
	v_rcp_f32_e32 v147, v147
	v_mul_f32_e32 v145, v150, v145
	v_mul_f32_e32 v150, 0xbfb8aa3b, v140
	v_exp_f32_e32 v150, v150
	v_mul_f32_e32 v147, v151, v147
	v_add_f32_e32 v150, 1.0, v150
	v_rcp_f32_e32 v150, v150
	s_nop 0
	v_mul_f32_e32 v150, v140, v150
	v_mul_f32_e32 v140, 0xbfb8aa3b, v148
	v_exp_f32_e32 v140, v140
	s_nop 0
	v_add_f32_e32 v140, 1.0, v140
	v_rcp_f32_e32 v140, v140
	s_nop 0
	v_mul_f32_e32 v148, v148, v140
	v_mul_f32_e32 v140, 0xbfb8aa3b, v141
	v_exp_f32_e32 v140, v140
	s_nop 0
	v_add_f32_e32 v140, 1.0, v140
	v_rcp_f32_e32 v140, v140
	s_nop 0
	v_mul_f32_e32 v141, v141, v140
	v_mul_f32_e32 v140, 0xbfb8aa3b, v149
	v_exp_f32_e32 v140, v140
	s_nop 0
	v_add_f32_e32 v140, 1.0, v140
	v_rcp_f32_e32 v140, v140
	s_nop 0
	v_mul_f32_e32 v149, v149, v140
	v_cvt_pk_bf16_f32 v140, v142, v143
	v_cvt_pk_bf16_f32 v141, v150, v141
	v_cvt_pk_bf16_f32 v142, v145, v147
	v_cvt_pk_bf16_f32 v143, v148, v149
	global_store_dwordx4 v[138:139], v[140:143], off sc1
	v_pk_mul_f32 v[148:149], v[70:71], v[144:145] op_sel_hi:[1,0]
	s_nop 0
	v_pk_mul_f32 v[142:143], v[72:73], v[144:145] op_sel_hi:[1,0]
	v_pk_mul_f32 v[140:141], v[74:75], v[144:145] op_sel_hi:[1,0]
	v_mul_f32_e32 v147, 0xbfb8aa3b, v142
	v_exp_f32_e32 v147, v147
	v_pk_mul_f32 v[144:145], v[68:69], v[144:145] op_sel_hi:[1,0]
	v_add_f32_e32 v147, 1.0, v147
	v_rcp_f32_e32 v147, v147
	s_nop 0
	v_mul_f32_e32 v142, v142, v147
	v_mul_f32_e32 v147, 0xbfb8aa3b, v144
	v_exp_f32_e32 v147, v147
	s_nop 0
	v_add_f32_e32 v147, 1.0, v147
	v_rcp_f32_e32 v147, v147
	s_nop 0
	v_mul_f32_e32 v144, v144, v147
	v_mul_f32_e32 v147, 0xbfb8aa3b, v143
	v_exp_f32_e32 v147, v147
	s_nop 0
	v_add_f32_e32 v147, 1.0, v147
	v_rcp_f32_e32 v147, v147
	s_nop 0
	v_mul_f32_e32 v143, v143, v147
	v_mul_f32_e32 v147, 0xbfb8aa3b, v145
	v_exp_f32_e32 v147, v147
	s_nop 0
	v_add_f32_e32 v147, 1.0, v147
	v_rcp_f32_e32 v147, v147
	s_nop 0
	v_mul_f32_e32 v145, v145, v147
	v_mul_f32_e32 v147, 0xbfb8aa3b, v140
	v_exp_f32_e32 v147, v147
	s_nop 0
	v_add_f32_e32 v147, 1.0, v147
	v_rcp_f32_e32 v147, v147
	s_nop 0
	v_mul_f32_e32 v147, v140, v147
	v_mul_f32_e32 v140, 0xbfb8aa3b, v148
	v_exp_f32_e32 v140, v140
	s_nop 0
	v_add_f32_e32 v140, 1.0, v140
	v_rcp_f32_e32 v140, v140
	s_nop 0
	v_mul_f32_e32 v148, v148, v140
	v_mul_f32_e32 v140, 0xbfb8aa3b, v141
	v_exp_f32_e32 v140, v140
	s_nop 0
	v_add_f32_e32 v140, 1.0, v140
	v_rcp_f32_e32 v140, v140
	s_nop 0
	v_mul_f32_e32 v141, v141, v140
	v_mul_f32_e32 v140, 0xbfb8aa3b, v149
	v_exp_f32_e32 v140, v140
	s_nop 0
	v_add_f32_e32 v140, 1.0, v140
	v_rcp_f32_e32 v140, v140
	s_nop 0
	v_mul_f32_e32 v149, v149, v140
	v_cvt_pk_bf16_f32 v140, v142, v143
	v_cvt_pk_bf16_f32 v141, v147, v141
	v_cvt_pk_bf16_f32 v142, v144, v145
	v_cvt_pk_bf16_f32 v143, v148, v149
	global_store_dwordx4 v[138:139], v[140:143], off offset:256 sc1
	v_fmamk_f32 v138, v209, 0x3a000000, v200
	v_cmp_gt_f32_e32 vcc, s91, v138
	v_mul_f32_e32 v139, 0x4b800000, v138
	s_nop 0
	v_cndmask_b32_e32 v138, v138, v139, vcc
	v_rsq_f32_e32 v138, v138
	s_nop 0
	v_mul_f32_e32 v139, 0x45800000, v138
	v_cndmask_b32_e32 v144, v138, v139, vcc
	v_pk_mul_f32 v[142:143], v[64:65], v[144:145] op_sel_hi:[1,0]
	v_pk_mul_f32 v[140:141], v[66:67], v[144:145] op_sel_hi:[1,0]
	v_pk_mul_f32 v[148:149], v[62:63], v[144:145] op_sel_hi:[1,0]
	v_pk_mul_f32 v[150:151], v[60:61], v[144:145] op_sel_hi:[1,0]
	v_mul_f32_e32 v145, 0xbfb8aa3b, v142
	v_exp_f32_e32 v145, v145
	v_mul_f32_e32 v147, 0xbfb8aa3b, v143
	v_exp_f32_e32 v147, v147
	v_lshlrev_b64 v[138:139], 12, v[188:189]
	v_add_f32_e32 v145, 1.0, v145
	v_rcp_f32_e32 v145, v145
	v_add_f32_e32 v147, 1.0, v147
	v_rcp_f32_e32 v147, v147
	v_lshl_add_u64 v[138:139], v[136:137], 0, v[138:139]
	v_mul_f32_e32 v142, v142, v145
	v_mul_f32_e32 v145, 0xbfb8aa3b, v150
	v_exp_f32_e32 v145, v145
	v_mul_f32_e32 v143, v143, v147
	v_mul_f32_e32 v147, 0xbfb8aa3b, v151
	v_exp_f32_e32 v147, v147
	v_add_f32_e32 v145, 1.0, v145
	v_rcp_f32_e32 v145, v145
	v_lshl_add_u64 v[136:137], v[134:135], 0, s[0:1]
	v_add_f32_e32 v147, 1.0, v147
	v_rcp_f32_e32 v147, v147
	v_mul_f32_e32 v145, v150, v145
	v_mul_f32_e32 v150, 0xbfb8aa3b, v140
	v_exp_f32_e32 v150, v150
	v_mul_f32_e32 v147, v151, v147
	s_mov_b32 s0, 0x90000
	v_add_f32_e32 v150, 1.0, v150
	v_rcp_f32_e32 v150, v150
	s_nop 0
	v_mul_f32_e32 v150, v140, v150
	v_mul_f32_e32 v140, 0xbfb8aa3b, v148
	v_exp_f32_e32 v140, v140
	s_nop 0
	v_add_f32_e32 v140, 1.0, v140
	v_rcp_f32_e32 v140, v140
	s_nop 0
	v_mul_f32_e32 v148, v148, v140
	v_mul_f32_e32 v140, 0xbfb8aa3b, v141
	v_exp_f32_e32 v140, v140
	s_nop 0
	v_add_f32_e32 v140, 1.0, v140
	v_rcp_f32_e32 v140, v140
	s_nop 0
	v_mul_f32_e32 v141, v141, v140
	v_mul_f32_e32 v140, 0xbfb8aa3b, v149
	v_exp_f32_e32 v140, v140
	s_nop 0
	v_add_f32_e32 v140, 1.0, v140
	v_rcp_f32_e32 v140, v140
	s_nop 0
	v_mul_f32_e32 v149, v149, v140
	v_cvt_pk_bf16_f32 v140, v142, v143
	v_cvt_pk_bf16_f32 v141, v150, v141
	v_cvt_pk_bf16_f32 v142, v145, v147
	v_cvt_pk_bf16_f32 v143, v148, v149
	global_store_dwordx4 v[138:139], v[140:143], off sc1
	v_pk_mul_f32 v[148:149], v[30:31], v[144:145] op_sel_hi:[1,0]
	s_nop 0
	v_pk_mul_f32 v[142:143], v[32:33], v[144:145] op_sel_hi:[1,0]
	v_pk_mul_f32 v[140:141], v[34:35], v[144:145] op_sel_hi:[1,0]
	v_mul_f32_e32 v147, 0xbfb8aa3b, v142
	v_exp_f32_e32 v147, v147
	v_pk_mul_f32 v[144:145], v[28:29], v[144:145] op_sel_hi:[1,0]
	v_add_f32_e32 v147, 1.0, v147
	v_rcp_f32_e32 v147, v147
	s_nop 0
	v_mul_f32_e32 v142, v142, v147
	v_mul_f32_e32 v147, 0xbfb8aa3b, v144
	v_exp_f32_e32 v147, v147
	s_nop 0
	v_add_f32_e32 v147, 1.0, v147
	v_rcp_f32_e32 v147, v147
	s_nop 0
	v_mul_f32_e32 v144, v144, v147
	v_mul_f32_e32 v147, 0xbfb8aa3b, v143
	v_exp_f32_e32 v147, v147
	s_nop 0
	v_add_f32_e32 v147, 1.0, v147
	v_rcp_f32_e32 v147, v147
	s_nop 0
	v_mul_f32_e32 v143, v143, v147
	v_mul_f32_e32 v147, 0xbfb8aa3b, v145
	v_exp_f32_e32 v147, v147
	s_nop 0
	v_add_f32_e32 v147, 1.0, v147
	v_rcp_f32_e32 v147, v147
	s_nop 0
	v_mul_f32_e32 v145, v145, v147
	v_mul_f32_e32 v147, 0xbfb8aa3b, v140
	v_exp_f32_e32 v147, v147
	s_nop 0
	v_add_f32_e32 v147, 1.0, v147
	v_rcp_f32_e32 v147, v147
	s_nop 0
	v_mul_f32_e32 v147, v140, v147
	v_mul_f32_e32 v140, 0xbfb8aa3b, v148
	v_exp_f32_e32 v140, v140
	s_nop 0
	v_add_f32_e32 v140, 1.0, v140
	v_rcp_f32_e32 v140, v140
	s_nop 0
	v_mul_f32_e32 v148, v148, v140
	v_mul_f32_e32 v140, 0xbfb8aa3b, v141
	v_exp_f32_e32 v140, v140
	s_nop 0
	v_add_f32_e32 v140, 1.0, v140
	v_rcp_f32_e32 v140, v140
	s_nop 0
	v_mul_f32_e32 v141, v141, v140
	v_mul_f32_e32 v140, 0xbfb8aa3b, v149
	v_exp_f32_e32 v140, v140
	s_nop 0
	v_add_f32_e32 v140, 1.0, v140
	v_rcp_f32_e32 v140, v140
	s_nop 0
	v_mul_f32_e32 v149, v149, v140
	v_cvt_pk_bf16_f32 v140, v142, v143
	v_cvt_pk_bf16_f32 v141, v147, v141
	v_cvt_pk_bf16_f32 v142, v144, v145
	v_cvt_pk_bf16_f32 v143, v148, v149
	global_store_dwordx4 v[138:139], v[140:143], off offset:256 sc1
	v_fmamk_f32 v138, v208, 0x3a000000, v200
	v_cmp_gt_f32_e32 vcc, s91, v138
	v_mul_f32_e32 v139, 0x4b800000, v138
	s_nop 0
	v_cndmask_b32_e32 v138, v138, v139, vcc
	v_rsq_f32_e32 v138, v138
	s_nop 0
	v_mul_f32_e32 v139, 0x45800000, v138
	v_cndmask_b32_e32 v142, v138, v139, vcc
	v_pk_mul_f32 v[140:141], v[56:57], v[142:143] op_sel_hi:[1,0]
	v_pk_mul_f32 v[138:139], v[58:59], v[142:143] op_sel_hi:[1,0]
	v_pk_mul_f32 v[144:145], v[54:55], v[142:143] op_sel_hi:[1,0]
	v_pk_mul_f32 v[148:149], v[52:53], v[142:143] op_sel_hi:[1,0]
	v_mul_f32_e32 v143, 0xbfb8aa3b, v140
	v_exp_f32_e32 v143, v143
	v_mul_f32_e32 v147, 0xbfb8aa3b, v141
	v_exp_f32_e32 v147, v147
	v_add_f32_e32 v143, 1.0, v143
	v_rcp_f32_e32 v143, v143
	v_add_f32_e32 v147, 1.0, v147
	v_rcp_f32_e32 v147, v147
	v_mul_f32_e32 v140, v140, v143
	v_mul_f32_e32 v143, 0xbfb8aa3b, v148
	v_exp_f32_e32 v143, v143
	v_mul_f32_e32 v141, v141, v147
	v_mul_f32_e32 v147, 0xbfb8aa3b, v149
	v_exp_f32_e32 v147, v147
	v_add_f32_e32 v143, 1.0, v143
	v_rcp_f32_e32 v143, v143
	v_add_f32_e32 v147, 1.0, v147
	v_rcp_f32_e32 v147, v147
	v_mul_f32_e32 v143, v148, v143
	v_mul_f32_e32 v148, 0xbfb8aa3b, v138
	v_exp_f32_e32 v148, v148
	v_mul_f32_e32 v147, v149, v147
	v_add_f32_e32 v148, 1.0, v148
	v_rcp_f32_e32 v148, v148
	s_nop 0
	v_mul_f32_e32 v148, v138, v148
	v_mul_f32_e32 v138, 0xbfb8aa3b, v144
	v_exp_f32_e32 v138, v138
	s_nop 0
	v_add_f32_e32 v138, 1.0, v138
	v_rcp_f32_e32 v138, v138
	s_nop 0
	v_mul_f32_e32 v144, v144, v138
	v_mul_f32_e32 v138, 0xbfb8aa3b, v139
	v_exp_f32_e32 v138, v138
	s_nop 0
	v_add_f32_e32 v138, 1.0, v138
	v_rcp_f32_e32 v138, v138
	s_nop 0
	v_mul_f32_e32 v139, v139, v138
	v_mul_f32_e32 v138, 0xbfb8aa3b, v145
	v_exp_f32_e32 v138, v138
	s_nop 0
	v_add_f32_e32 v138, 1.0, v138
	v_rcp_f32_e32 v138, v138
	s_nop 0
	v_mul_f32_e32 v145, v145, v138
	v_cvt_pk_bf16_f32 v138, v140, v141
	v_cvt_pk_bf16_f32 v139, v148, v139
	v_cvt_pk_bf16_f32 v140, v143, v147
	v_cvt_pk_bf16_f32 v141, v144, v145
	v_add_co_u32_e32 v144, vcc, s0, v134
	s_mov_b64 s[0:1], 0xa0000
	s_nop 0
	v_addc_co_u32_e32 v145, vcc, 0, v135, vcc
	global_store_dwordx4 v[144:145], v[138:141], off sc1
	v_pk_mul_f32 v[144:145], v[22:23], v[142:143] op_sel_hi:[1,0]
	s_nop 0
	v_pk_mul_f32 v[140:141], v[24:25], v[142:143] op_sel_hi:[1,0]
	v_pk_mul_f32 v[138:139], v[26:27], v[142:143] op_sel_hi:[1,0]
	v_mul_f32_e32 v147, 0xbfb8aa3b, v140
	v_exp_f32_e32 v147, v147
	v_pk_mul_f32 v[142:143], v[20:21], v[142:143] op_sel_hi:[1,0]
	v_add_f32_e32 v147, 1.0, v147
	v_rcp_f32_e32 v147, v147
	s_nop 0
	v_mul_f32_e32 v140, v140, v147
	v_mul_f32_e32 v147, 0xbfb8aa3b, v142
	v_exp_f32_e32 v147, v147
	s_nop 0
	v_add_f32_e32 v147, 1.0, v147
	v_rcp_f32_e32 v147, v147
	s_nop 0
	v_mul_f32_e32 v142, v142, v147
	v_mul_f32_e32 v147, 0xbfb8aa3b, v141
	v_exp_f32_e32 v147, v147
	s_nop 0
	v_add_f32_e32 v147, 1.0, v147
	v_rcp_f32_e32 v147, v147
	s_nop 0
	v_mul_f32_e32 v141, v141, v147
	v_mul_f32_e32 v147, 0xbfb8aa3b, v143
	v_exp_f32_e32 v147, v147
	s_nop 0
	v_add_f32_e32 v147, 1.0, v147
	v_rcp_f32_e32 v147, v147
	s_nop 0
	v_mul_f32_e32 v143, v143, v147
	v_mul_f32_e32 v147, 0xbfb8aa3b, v138
	v_exp_f32_e32 v147, v147
	s_nop 0
	v_add_f32_e32 v147, 1.0, v147
	v_rcp_f32_e32 v147, v147
	s_nop 0
	v_mul_f32_e32 v147, v138, v147
	v_mul_f32_e32 v138, 0xbfb8aa3b, v144
	v_exp_f32_e32 v138, v138
	s_nop 0
	v_add_f32_e32 v138, 1.0, v138
	v_rcp_f32_e32 v138, v138
	s_nop 0
	v_mul_f32_e32 v144, v144, v138
	v_mul_f32_e32 v138, 0xbfb8aa3b, v139
	v_exp_f32_e32 v138, v138
	s_nop 0
	v_add_f32_e32 v138, 1.0, v138
	v_rcp_f32_e32 v138, v138
	s_nop 0
	v_mul_f32_e32 v139, v139, v138
	v_mul_f32_e32 v138, 0xbfb8aa3b, v145
	v_exp_f32_e32 v138, v138
	s_nop 0
	v_add_f32_e32 v138, 1.0, v138
	v_rcp_f32_e32 v138, v138
	s_nop 0
	v_mul_f32_e32 v145, v145, v138
	v_cvt_pk_bf16_f32 v138, v140, v141
	v_cvt_pk_bf16_f32 v139, v147, v139
	v_cvt_pk_bf16_f32 v140, v142, v143
	v_cvt_pk_bf16_f32 v141, v144, v145
	global_store_dwordx4 v[136:137], v[138:141], off offset:256 sc1
	v_fmamk_f32 v136, v207, 0x3a000000, v200
	v_cmp_gt_f32_e32 vcc, s91, v136
	v_mul_f32_e32 v137, 0x4b800000, v136
	s_nop 0
	v_cndmask_b32_e32 v136, v136, v137, vcc
	v_rsq_f32_e32 v136, v136
	s_nop 0
	v_mul_f32_e32 v137, 0x45800000, v136
	v_cndmask_b32_e32 v142, v136, v137, vcc
	v_pk_mul_f32 v[140:141], v[48:49], v[142:143] op_sel_hi:[1,0]
	v_pk_mul_f32 v[138:139], v[50:51], v[142:143] op_sel_hi:[1,0]
	v_pk_mul_f32 v[144:145], v[46:47], v[142:143] op_sel_hi:[1,0]
	v_pk_mul_f32 v[148:149], v[44:45], v[142:143] op_sel_hi:[1,0]
	v_mul_f32_e32 v143, 0xbfb8aa3b, v140
	v_exp_f32_e32 v143, v143
	v_mul_f32_e32 v147, 0xbfb8aa3b, v141
	v_exp_f32_e32 v147, v147
	v_lshl_add_u64 v[136:137], v[134:135], 0, s[0:1]
	v_add_f32_e32 v143, 1.0, v143
	v_rcp_f32_e32 v143, v143
	v_add_f32_e32 v147, 1.0, v147
	v_rcp_f32_e32 v147, v147
	s_mov_b32 s0, 0xa0000
	v_mul_f32_e32 v140, v140, v143
	v_mul_f32_e32 v143, 0xbfb8aa3b, v148
	v_exp_f32_e32 v143, v143
	v_mul_f32_e32 v141, v141, v147
	v_mul_f32_e32 v147, 0xbfb8aa3b, v149
	v_exp_f32_e32 v147, v147
	v_add_f32_e32 v143, 1.0, v143
	v_rcp_f32_e32 v143, v143
	v_add_f32_e32 v147, 1.0, v147
	v_rcp_f32_e32 v147, v147
	v_mul_f32_e32 v143, v148, v143
	v_mul_f32_e32 v148, 0xbfb8aa3b, v138
	v_exp_f32_e32 v148, v148
	v_mul_f32_e32 v147, v149, v147
	v_add_f32_e32 v148, 1.0, v148
	v_rcp_f32_e32 v148, v148
	s_nop 0
	v_mul_f32_e32 v148, v138, v148
	v_mul_f32_e32 v138, 0xbfb8aa3b, v144
	v_exp_f32_e32 v138, v138
	s_nop 0
	v_add_f32_e32 v138, 1.0, v138
	v_rcp_f32_e32 v138, v138
	s_nop 0
	v_mul_f32_e32 v144, v144, v138
	v_mul_f32_e32 v138, 0xbfb8aa3b, v139
	v_exp_f32_e32 v138, v138
	s_nop 0
	v_add_f32_e32 v138, 1.0, v138
	v_rcp_f32_e32 v138, v138
	s_nop 0
	v_mul_f32_e32 v139, v139, v138
	v_mul_f32_e32 v138, 0xbfb8aa3b, v145
	v_exp_f32_e32 v138, v138
	s_nop 0
	v_add_f32_e32 v138, 1.0, v138
	v_rcp_f32_e32 v138, v138
	s_nop 0
	v_mul_f32_e32 v145, v145, v138
	v_cvt_pk_bf16_f32 v138, v140, v141
	v_cvt_pk_bf16_f32 v139, v148, v139
	v_cvt_pk_bf16_f32 v140, v143, v147
	v_cvt_pk_bf16_f32 v141, v144, v145
	v_add_co_u32_e32 v144, vcc, s0, v134
	s_mov_b64 s[0:1], 0xb0000
	s_nop 0
	v_addc_co_u32_e32 v145, vcc, 0, v135, vcc
	global_store_dwordx4 v[144:145], v[138:141], off sc1
	v_pk_mul_f32 v[144:145], v[14:15], v[142:143] op_sel_hi:[1,0]
	s_nop 0
	v_pk_mul_f32 v[140:141], v[16:17], v[142:143] op_sel_hi:[1,0]
	v_pk_mul_f32 v[138:139], v[18:19], v[142:143] op_sel_hi:[1,0]
	v_mul_f32_e32 v147, 0xbfb8aa3b, v140
	v_exp_f32_e32 v147, v147
	v_pk_mul_f32 v[142:143], v[12:13], v[142:143] op_sel_hi:[1,0]
	v_add_f32_e32 v147, 1.0, v147
	v_rcp_f32_e32 v147, v147
	s_nop 0
	v_mul_f32_e32 v140, v140, v147
	v_mul_f32_e32 v147, 0xbfb8aa3b, v142
	v_exp_f32_e32 v147, v147
	s_nop 0
	v_add_f32_e32 v147, 1.0, v147
	v_rcp_f32_e32 v147, v147
	s_nop 0
	v_mul_f32_e32 v142, v142, v147
	v_mul_f32_e32 v147, 0xbfb8aa3b, v141
	v_exp_f32_e32 v147, v147
	s_nop 0
	v_add_f32_e32 v147, 1.0, v147
	v_rcp_f32_e32 v147, v147
	s_nop 0
	v_mul_f32_e32 v141, v141, v147
	v_mul_f32_e32 v147, 0xbfb8aa3b, v143
	v_exp_f32_e32 v147, v147
	s_nop 0
	v_add_f32_e32 v147, 1.0, v147
	v_rcp_f32_e32 v147, v147
	s_nop 0
	v_mul_f32_e32 v143, v143, v147
	v_mul_f32_e32 v147, 0xbfb8aa3b, v138
	v_exp_f32_e32 v147, v147
	s_nop 0
	v_add_f32_e32 v147, 1.0, v147
	v_rcp_f32_e32 v147, v147
	s_nop 0
	v_mul_f32_e32 v147, v138, v147
	v_mul_f32_e32 v138, 0xbfb8aa3b, v144
	v_exp_f32_e32 v138, v138
	s_nop 0
	v_add_f32_e32 v138, 1.0, v138
	v_rcp_f32_e32 v138, v138
	s_nop 0
	v_mul_f32_e32 v144, v144, v138
	v_mul_f32_e32 v138, 0xbfb8aa3b, v139
	v_exp_f32_e32 v138, v138
	s_nop 0
	v_add_f32_e32 v138, 1.0, v138
	v_rcp_f32_e32 v138, v138
	s_nop 0
	v_mul_f32_e32 v139, v139, v138
	v_mul_f32_e32 v138, 0xbfb8aa3b, v145
	v_exp_f32_e32 v138, v138
	s_nop 0
	v_add_f32_e32 v138, 1.0, v138
	v_rcp_f32_e32 v138, v138
	s_nop 0
	v_mul_f32_e32 v145, v145, v138
	v_cvt_pk_bf16_f32 v138, v140, v141
	v_cvt_pk_bf16_f32 v139, v147, v139
	v_cvt_pk_bf16_f32 v140, v142, v143
	v_cvt_pk_bf16_f32 v141, v144, v145
	global_store_dwordx4 v[136:137], v[138:141], off offset:256 sc1
	v_fmamk_f32 v136, v206, 0x3a000000, v200
	v_cmp_gt_f32_e32 vcc, s91, v136
	v_mul_f32_e32 v137, 0x4b800000, v136
	s_nop 0
	v_cndmask_b32_e32 v136, v136, v137, vcc
	v_rsq_f32_e32 v136, v136
	s_nop 0
	v_mul_f32_e32 v137, 0x45800000, v136
	v_cndmask_b32_e32 v142, v136, v137, vcc
	v_pk_mul_f32 v[140:141], v[40:41], v[142:143] op_sel_hi:[1,0]
	v_pk_mul_f32 v[138:139], v[42:43], v[142:143] op_sel_hi:[1,0]
	v_pk_mul_f32 v[144:145], v[38:39], v[142:143] op_sel_hi:[1,0]
	v_pk_mul_f32 v[148:149], v[36:37], v[142:143] op_sel_hi:[1,0]
	v_mul_f32_e32 v143, 0xbfb8aa3b, v140
	v_exp_f32_e32 v143, v143
	v_mul_f32_e32 v147, 0xbfb8aa3b, v141
	v_exp_f32_e32 v147, v147
	v_lshl_add_u64 v[136:137], v[134:135], 0, s[0:1]
	v_add_f32_e32 v143, 1.0, v143
	v_rcp_f32_e32 v143, v143
	v_add_f32_e32 v147, 1.0, v147
	v_rcp_f32_e32 v147, v147
	s_mov_b32 s0, 0xb0000
	v_mul_f32_e32 v140, v140, v143
	v_mul_f32_e32 v143, 0xbfb8aa3b, v148
	v_exp_f32_e32 v143, v143
	v_mul_f32_e32 v141, v141, v147
	v_mul_f32_e32 v147, 0xbfb8aa3b, v149
	v_exp_f32_e32 v147, v147
	v_add_f32_e32 v143, 1.0, v143
	v_rcp_f32_e32 v143, v143
	v_add_co_u32_e32 v134, vcc, s0, v134
	v_add_f32_e32 v147, 1.0, v147
	v_mul_f32_e32 v143, v148, v143
	v_mul_f32_e32 v148, 0xbfb8aa3b, v138
	v_exp_f32_e32 v148, v148
	v_rcp_f32_e32 v147, v147
	v_addc_co_u32_e32 v135, vcc, 0, v135, vcc
	v_add_f32_e32 v148, 1.0, v148
	v_rcp_f32_e32 v148, v148
	v_mul_f32_e32 v147, v149, v147
	s_mov_b64 s[0:1], 0
	v_mul_f32_e32 v148, v138, v148
	v_mul_f32_e32 v138, 0xbfb8aa3b, v144
	v_exp_f32_e32 v138, v138
	s_nop 0
	v_add_f32_e32 v138, 1.0, v138
	v_rcp_f32_e32 v138, v138
	s_nop 0
	v_mul_f32_e32 v144, v144, v138
	v_mul_f32_e32 v138, 0xbfb8aa3b, v139
	v_exp_f32_e32 v138, v138
	s_nop 0
	v_add_f32_e32 v138, 1.0, v138
	v_rcp_f32_e32 v138, v138
	s_nop 0
	v_mul_f32_e32 v139, v139, v138
	v_mul_f32_e32 v138, 0xbfb8aa3b, v145
	v_exp_f32_e32 v138, v138
	s_nop 0
	v_add_f32_e32 v138, 1.0, v138
	v_rcp_f32_e32 v138, v138
	s_nop 0
	v_mul_f32_e32 v145, v145, v138
	v_cvt_pk_bf16_f32 v138, v140, v141
	v_cvt_pk_bf16_f32 v139, v148, v139
	v_cvt_pk_bf16_f32 v140, v143, v147
	v_cvt_pk_bf16_f32 v141, v144, v145
	global_store_dwordx4 v[134:135], v[138:141], off sc1
	v_pk_mul_f32 v[134:135], v[10:11], v[142:143] op_sel_hi:[1,0]
	s_nop 0
	v_pk_mul_f32 v[138:139], v[8:9], v[142:143] op_sel_hi:[1,0]
	v_pk_mul_f32 v[140:141], v[6:7], v[142:143] op_sel_hi:[1,0]
	v_mul_f32_e32 v144, 0xbfb8aa3b, v138
	v_exp_f32_e32 v144, v144
	v_pk_mul_f32 v[142:143], v[4:5], v[142:143] op_sel_hi:[1,0]
	v_add_f32_e32 v144, 1.0, v144
	v_rcp_f32_e32 v144, v144
	s_nop 0
	v_mul_f32_e32 v138, v138, v144
	v_mul_f32_e32 v144, 0xbfb8aa3b, v142
	v_exp_f32_e32 v144, v144
	s_nop 0
	v_add_f32_e32 v144, 1.0, v144
	v_rcp_f32_e32 v144, v144
	s_nop 0
	v_mul_f32_e32 v142, v142, v144
	v_mul_f32_e32 v144, 0xbfb8aa3b, v139
	v_exp_f32_e32 v144, v144
	s_nop 0
	v_add_f32_e32 v144, 1.0, v144
	v_rcp_f32_e32 v144, v144
	s_nop 0
	v_mul_f32_e32 v139, v139, v144
	v_mul_f32_e32 v144, 0xbfb8aa3b, v143
	v_exp_f32_e32 v144, v144
	v_cvt_pk_bf16_f32 v138, v138, v139
	s_nop 0
	v_add_f32_e32 v144, 1.0, v144
	v_rcp_f32_e32 v144, v144
	s_nop 0
	v_mul_f32_e32 v143, v143, v144
	v_mul_f32_e32 v144, 0xbfb8aa3b, v134
	v_exp_f32_e32 v144, v144
	s_nop 0
	v_add_f32_e32 v144, 1.0, v144
	v_rcp_f32_e32 v144, v144
	s_nop 0
	v_mul_f32_e32 v134, v134, v144
	v_mul_f32_e32 v144, 0xbfb8aa3b, v140
	v_exp_f32_e32 v144, v144
	s_nop 0
	v_add_f32_e32 v144, 1.0, v144
	v_rcp_f32_e32 v144, v144
	s_nop 0
	v_mul_f32_e32 v144, v140, v144
	v_mul_f32_e32 v140, 0xbfb8aa3b, v135
	v_exp_f32_e32 v140, v140
	s_nop 0
	v_add_f32_e32 v140, 1.0, v140
	v_rcp_f32_e32 v140, v140
	s_nop 0
	v_mul_f32_e32 v135, v135, v140
	v_mul_f32_e32 v140, 0xbfb8aa3b, v141
	v_exp_f32_e32 v140, v140
	v_cvt_pk_bf16_f32 v139, v134, v135
	s_nop 0
	v_add_f32_e32 v140, 1.0, v140
	v_rcp_f32_e32 v140, v140
	s_nop 0
	v_mul_f32_e32 v141, v141, v140
	v_cvt_pk_bf16_f32 v140, v142, v143
	v_cvt_pk_bf16_f32 v141, v144, v141
	global_store_dwordx4 v[136:137], v[138:141], off offset:256 sc1
